# PLACE4: attention tile loop (and everything after it) shifted by 4 bytes: loop start from 4 mod 8 to 0 mod 8 (on SO7)
# speedup vs baseline: 1.0020x; 1.0020x over previous
.LBB0_987:
	s_waitcnt lgkmcnt(0)
	v_add_f32_e32 v2, v2, v3
	v_mul_f32_e32 v3, 0x4f800000, v2
	v_cmp_gt_f32_e32 vcc, s36, v2
	s_lshl_b32 s26, s42, 7
	s_add_i32 s42, s29, 0x2000
	v_cndmask_b32_e32 v2, v2, v3, vcc
	v_sqrt_f32_e32 v3, v2
	v_mov_b32_e32 v139, 0
	v_lshl_add_u32 v141, s41, 13, v154
	v_mov_b32_e32 v7, v139
	v_add_u32_e32 v5, -1, v3
	v_fma_f32 v6, -v5, v3, v2
	v_cmp_ge_f32_e64 s[4:5], 0, v6
	v_add_u32_e32 v6, 1, v3
	v_mov_b32_e32 v8, v139
	v_cndmask_b32_e64 v5, v3, v5, s[4:5]
	v_fma_f32 v3, -v6, v3, v2
	v_cmp_lt_f32_e64 s[4:5], 0, v3
	v_mov_b32_e32 v9, v139
	v_mov_b32_e32 v10, v139
	v_cndmask_b32_e64 v3, v5, v6, s[4:5]
	v_mul_f32_e32 v5, 0x37800000, v3
	v_cndmask_b32_e32 v3, v3, v5, vcc
	v_cmp_class_f32_e32 vcc, v2, v156
	s_add_i32 s4, s44, 1
	s_and_b32 s5, s45, 0x3ffffff0
	v_cndmask_b32_e32 v2, v3, v2, vcc
	v_mul_f32_e64 v66, v2, -v4
	v_lshl_add_u64 v[2:3], s[22:23], 0, v[134:135]
	s_add_u32 s22, s6, s5
	s_addc_u32 s23, 0, 0
	v_lshl_add_u64 v[144:145], v[2:3], 0, s[22:23]
	s_add_u32 s22, s6, s28
	s_addc_u32 s23, 0, 0
	s_lshl_b32 s5, s43, 9
	s_and_b32 s5, s5, 0x18000
	v_lshl_or_b32 v4, v155, 1, s5
	v_mov_b32_e32 v5, v131
	v_lshl_add_u64 v[2:3], s[24:25], 0, v[136:137]
	v_lshl_add_u64 v[4:5], s[22:23], 0, v[4:5]
	v_mov_b32_e32 v67, v66
	v_mov_b32_e32 v68, v66
	v_mov_b32_e32 v69, v66
	v_mov_b32_e32 v70, v66
	v_mov_b32_e32 v71, v66
	v_mov_b32_e32 v72, v66
	v_mov_b32_e32 v73, v66
	v_mov_b32_e32 v74, v66
	v_mov_b32_e32 v75, v66
	v_mov_b32_e32 v76, v66
	v_mov_b32_e32 v77, v66
	v_mov_b32_e32 v78, v66
	v_mov_b32_e32 v79, v66
	v_mov_b32_e32 v80, v66
	v_mov_b32_e32 v81, v66
	v_lshl_add_u64 v[146:147], v[2:3], 0, v[4:5]
	s_mov_b32 s6, 0
	v_mov_b32_e32 v2, 0
	v_mov_b32_e32 v3, v139
	v_mov_b32_e32 v4, v139
	v_mov_b32_e32 v5, v139
	v_mov_b32_e32 v6, v139
	v_mov_b32_e32 v11, v139
	v_mov_b32_e32 v12, v139
	v_mov_b32_e32 v13, v139
	v_mov_b32_e32 v14, v139
	v_mov_b32_e32 v15, v139
	v_mov_b32_e32 v16, v139
	v_mov_b32_e32 v17, v139
	v_mov_b32_e32 v18, 0
	v_mov_b32_e32 v19, v139
	v_mov_b32_e32 v20, v139
	v_mov_b32_e32 v21, v139
	v_mov_b32_e32 v22, v139
	v_mov_b32_e32 v23, v139
	v_mov_b32_e32 v24, v139
	v_mov_b32_e32 v25, v139
	v_mov_b32_e32 v26, v139
	v_mov_b32_e32 v27, v139
	v_mov_b32_e32 v28, v139
	v_mov_b32_e32 v29, v139
	v_mov_b32_e32 v30, v139
	v_mov_b32_e32 v31, v139
	v_mov_b32_e32 v32, v139
	v_mov_b32_e32 v33, v139
	v_mov_b32_e32 v34, 0
	v_mov_b32_e32 v35, v139
	v_mov_b32_e32 v36, v139
	v_mov_b32_e32 v37, v139
	v_mov_b32_e32 v38, v139
	v_mov_b32_e32 v39, v139
	v_mov_b32_e32 v40, v139
	v_mov_b32_e32 v41, v139
	v_mov_b32_e32 v42, v139
	v_mov_b32_e32 v43, v139
	v_mov_b32_e32 v44, v139
	v_mov_b32_e32 v45, v139
	v_mov_b32_e32 v46, v139
	v_mov_b32_e32 v47, v139
	v_mov_b32_e32 v48, v139
	v_mov_b32_e32 v49, v139
	v_mov_b32_e32 v50, 0
	v_mov_b32_e32 v51, v139
	v_mov_b32_e32 v52, v139
	v_mov_b32_e32 v53, v139
	v_mov_b32_e32 v54, v139
	v_mov_b32_e32 v55, v139
	v_mov_b32_e32 v56, v139
	v_mov_b32_e32 v57, v139
	v_mov_b32_e32 v58, v139
	v_mov_b32_e32 v59, v139
	v_mov_b32_e32 v60, v139
	v_mov_b32_e32 v61, v139
	v_mov_b32_e32 v62, v139
	v_mov_b32_e32 v63, v139
	v_mov_b32_e32 v64, v139
	v_mov_b32_e32 v65, v139
	s_movk_i32 s23, 0x4000
	s_mov_b32 s28, m0
	s_add_i32 s24, s23, s29
	s_mov_b32 m0, s24
	s_add_i32 s25, s23, s42
	global_load_lds_dwordx4 v[144:145], off
	s_addk_i32 s25, 0xff80
	s_mov_b32 m0, s25
	s_add_i32 s24, s24, 0xc000
	global_load_lds_dwordx4 v[144:145], off offset:128
	s_mov_b32 m0, s24
	s_add_i32 s25, s25, 0xc000
	global_load_lds_dwordx4 v[146:147], off
	s_mov_b32 m0, s25
	v_lshl_add_u64 v[144:145], v[144:145], 0, s[18:19]
	global_load_lds_dwordx4 v[146:147], off offset:128
	s_mov_b32 m0, s28
	v_lshl_add_u64 v[146:147], v[146:147], 0, s[18:19]
	s_waitcnt vmcnt(4) lgkmcnt(0)
	s_barrier
	v_mov_b32_e32 v159, v141
	ds_read_b128 v[210:213], v159
	ds_read_b128 v[214:217], v159 offset:512
	ds_read_b128 v[218:221], v159 offset:2048
	ds_read_b128 v[222:225], v159 offset:2560
	ds_read_b128 v[226:229], v159 offset:4096
	ds_read_b128 v[230:233], v159 offset:4608
	ds_read_b128 v[234:237], v159 offset:6144
	ds_read_b128 v[238:241], v159 offset:6656
	s_waitcnt lgkmcnt(7)
	v_mfma_f32_32x32x16_bf16 v[98:113], v[210:213], v[126:129], v[66:81]
	s_waitcnt lgkmcnt(5)
	v_mfma_f32_32x32x16_bf16 v[98:113], v[218:221], v[122:125], v[98:113]
	s_waitcnt lgkmcnt(3)
	v_mfma_f32_32x32x16_bf16 v[98:113], v[226:229], v[118:121], v[98:113]
	s_waitcnt lgkmcnt(1)
	v_mfma_f32_32x32x16_bf16 v[98:113], v[234:237], v[114:117], v[98:113]
	v_mfma_f32_32x32x16_bf16 v[82:97], v[214:217], v[126:129], v[66:81]
	v_mfma_f32_32x32x16_bf16 v[82:97], v[222:225], v[122:125], v[82:97]
	v_mfma_f32_32x32x16_bf16 v[82:97], v[230:233], v[118:121], v[82:97]
	s_waitcnt lgkmcnt(0)
	v_mfma_f32_32x32x16_bf16 v[82:97], v[238:241], v[114:117], v[82:97]
	s_nop 6
	v_exp_f32_e32 v98, v98
	v_exp_f32_e32 v99, v99
	v_exp_f32_e32 v100, v100
	v_exp_f32_e32 v101, v101
	v_exp_f32_e32 v102, v102
	v_exp_f32_e32 v103, v103
	v_exp_f32_e32 v104, v104
	v_exp_f32_e32 v105, v105
	v_exp_f32_e32 v106, v106
	v_exp_f32_e32 v107, v107
	v_exp_f32_e32 v108, v108
	v_exp_f32_e32 v109, v109
	v_exp_f32_e32 v110, v110
	v_exp_f32_e32 v111, v111
	v_exp_f32_e32 v112, v112
	v_exp_f32_e32 v113, v113
	v_exp_f32_e32 v82, v82
	v_exp_f32_e32 v83, v83
	v_exp_f32_e32 v84, v84
	v_exp_f32_e32 v85, v85
	v_exp_f32_e32 v86, v86
	v_exp_f32_e32 v87, v87
	v_exp_f32_e32 v88, v88
	v_exp_f32_e32 v89, v89
	v_exp_f32_e32 v90, v90
	v_exp_f32_e32 v91, v91
	v_exp_f32_e32 v92, v92
	v_exp_f32_e32 v93, v93
	v_exp_f32_e32 v94, v94
	v_exp_f32_e32 v95, v95
	v_exp_f32_e32 v96, v96
	v_exp_f32_e32 v97, v97
	v_cvt_pk_bf16_f32 v194, v98, v99
	v_cvt_pk_bf16_f32 v195, v100, v101
	v_cvt_pk_bf16_f32 v196, v102, v103
	v_cvt_pk_bf16_f32 v197, v104, v105
	v_cvt_pk_bf16_f32 v198, v106, v107
	v_cvt_pk_bf16_f32 v199, v108, v109
	v_cvt_pk_bf16_f32 v200, v110, v111
	v_cvt_pk_bf16_f32 v201, v112, v113
	v_cvt_pk_bf16_f32 v202, v82, v83
	v_cvt_pk_bf16_f32 v203, v84, v85
	v_cvt_pk_bf16_f32 v204, v86, v87
	v_cvt_pk_bf16_f32 v205, v88, v89
	v_cvt_pk_bf16_f32 v206, v90, v91
	v_cvt_pk_bf16_f32 v207, v92, v93
	v_cvt_pk_bf16_f32 v208, v94, v95
	v_cvt_pk_bf16_f32 v209, v96, v97
	s_mov_b32 s6, 0
	s_nop 0
